# write-through (sc1) 16-byte stores for the outputs of P0 weight transposes, QK-norm projection epilogue and the A-layer combine (less dirty L2 to write back at the following grid barriers); on top of
# speedup vs baseline: 1.0074x; 1.0074x over previous
.LBB0_63:
	s_lshr_b32 s14, s4, 7
	v_cvt_f32_u32_e32 v0, s14
	s_sub_i32 s37, 0, s14
	s_abs_i32 s16, s17
	s_ashr_i32 s15, s17, 31
	v_rcp_iflag_f32_e32 v0, v0
	s_nop 0
	v_mul_f32_e32 v0, 0x4f7ffffe, v0
	v_cvt_u32_f32_e32 v0, v0
	s_nop 0
	v_readfirstlane_b32 s38, v0
	s_mul_i32 s37, s37, s38
	s_mul_hi_u32 s37, s38, s37
	s_add_i32 s38, s38, s37
	s_mul_hi_u32 s37, s16, s38
	s_mul_i32 s38, s37, s14
	s_sub_i32 s16, s16, s38
	s_add_i32 s39, s37, 1
	s_sub_i32 s38, s16, s14
	s_cmp_ge_u32 s16, s14
	s_cselect_b32 s37, s39, s37
	s_cselect_b32 s16, s38, s16
	s_add_i32 s38, s37, 1
	s_cmp_ge_u32 s16, s14
	s_cselect_b32 s16, s38, s37
	s_xor_b32 s16, s16, s15
	s_sub_i32 s15, s16, s15
	s_mul_i32 s16, s15, s14
	s_lshl_b32 s14, s15, 6
	v_or_b32_e32 v0, s14, v60
	s_ashr_i32 s15, s14, 31
	s_sub_i32 s16, s17, s16
	s_mul_i32 s17, s15, s4
	v_mad_u64_u32 v[0:1], s[38:39], v0, s4, 0
	s_lshl_b32 s16, s16, 7
	v_add_u32_e32 v1, s17, v1
	s_waitcnt lgkmcnt(0)
	v_lshl_add_u64 v[0:1], v[0:1], 2, s[18:19]
	s_ashr_i32 s17, s16, 31
	v_lshl_add_u64 v[0:1], s[16:17], 2, v[0:1]
	v_lshl_add_u64 v[4:5], v[0:1], 0, v[56:57]
	s_lshl_b64 s[18:19], s[4:5], 3
	v_lshl_add_u64 v[8:9], v[4:5], 0, s[18:19]
	global_load_dwordx4 v[0:3], v[4:5], off
	v_lshl_add_u64 v[12:13], v[8:9], 0, s[18:19]
	global_load_dwordx4 v[4:7], v[8:9], off
	s_mul_i32 s4, s12, s17
	global_load_dwordx4 v[8:11], v[12:13], off
	v_lshl_add_u64 v[12:13], v[12:13], 0, s[18:19]
	global_load_dwordx4 v[20:23], v[12:13], off
	v_lshl_add_u64 v[12:13], v[12:13], 0, s[18:19]
	v_lshl_add_u64 v[14:15], v[12:13], 0, s[18:19]
	global_load_dwordx4 v[40:43], v[12:13], off
	global_load_dwordx4 v[48:51], v[14:15], off
	v_lshl_add_u64 v[12:13], v[14:15], 0, s[18:19]
	v_lshl_add_u64 v[14:15], v[12:13], 0, s[18:19]
	global_load_dwordx4 v[66:69], v[12:13], off
	global_load_dwordx4 v[70:73], v[14:15], off
	v_lshl_add_u64 v[12:13], v[14:15], 0, s[18:19]
	global_load_dwordx4 v[74:77], v[12:13], off
	v_lshl_add_u64 v[12:13], v[12:13], 0, s[18:19]
	global_load_dwordx4 v[78:81], v[12:13], off
	v_lshl_add_u64 v[12:13], v[12:13], 0, s[18:19]
	global_load_dwordx4 v[82:85], v[12:13], off
	v_lshl_add_u64 v[12:13], v[12:13], 0, s[18:19]
	global_load_dwordx4 v[86:89], v[12:13], off
	v_lshl_add_u64 v[12:13], v[12:13], 0, s[18:19]
	global_load_dwordx4 v[90:93], v[12:13], off
	v_lshl_add_u64 v[12:13], v[12:13], 0, s[18:19]
	global_load_dwordx4 v[94:97], v[12:13], off
	v_lshl_add_u64 v[14:15], v[12:13], 0, s[18:19]
	global_load_dwordx4 v[98:101], v[14:15], off
	v_lshl_add_u64 v[12:13], v[14:15], 0, s[18:19]
	global_load_dwordx4 v[102:105], v[12:13], off
	v_lshl_add_u64 v[14:15], v[12:13], 0, s[18:19]
	global_load_dwordx4 v[106:109], v[14:15], off
	v_lshl_add_u64 v[12:13], v[14:15], 0, s[18:19]
	global_load_dwordx4 v[110:113], v[12:13], off
	v_lshl_add_u64 v[14:15], v[12:13], 0, s[18:19]
	global_load_dwordx4 v[114:117], v[14:15], off
	v_lshl_add_u64 v[12:13], v[14:15], 0, s[18:19]
	global_load_dwordx4 v[118:121], v[12:13], off
	v_lshl_add_u64 v[14:15], v[12:13], 0, s[18:19]
	global_load_dwordx4 v[122:125], v[14:15], off
	v_lshl_add_u64 v[12:13], v[14:15], 0, s[18:19]
	global_load_dwordx4 v[126:129], v[12:13], off
	v_lshl_add_u64 v[14:15], v[12:13], 0, s[18:19]
	global_load_dwordx4 v[130:133], v[14:15], off
	v_lshl_add_u64 v[12:13], v[14:15], 0, s[18:19]
	global_load_dwordx4 v[134:137], v[12:13], off
	v_lshl_add_u64 v[14:15], v[12:13], 0, s[18:19]
	v_lshl_add_u64 v[12:13], v[14:15], 0, s[18:19]
	global_load_dwordx4 v[138:141], v[14:15], off
	v_lshl_add_u64 v[14:15], v[12:13], 0, s[18:19]
	global_load_dwordx4 v[52:55], v[12:13], off
	v_lshl_add_u64 v[12:13], v[14:15], 0, s[18:19]
	global_load_dwordx4 v[44:47], v[14:15], off
	v_lshl_add_u64 v[14:15], v[12:13], 0, s[18:19]
	global_load_dwordx4 v[36:39], v[12:13], off
	v_lshl_add_u64 v[12:13], v[14:15], 0, s[18:19]
	global_load_dwordx4 v[32:35], v[14:15], off
	v_lshl_add_u64 v[14:15], v[12:13], 0, s[18:19]
	global_load_dwordx4 v[28:31], v[12:13], off
	v_lshl_add_u64 v[12:13], v[14:15], 0, s[18:19]
	global_load_dwordx4 v[16:19], v[14:15], off
	s_nop 0
	global_load_dwordx4 v[12:15], v[12:13], off
	s_add_i32 s36, s36, 1
	s_add_i32 s2, s2, s3
	s_waitcnt vmcnt(31)
	v_permlane32_swap_b32_e32 v0, v1
	v_permlane32_swap_b32_e32 v2, v3
	v_cvt_pk_bf16_f32 v24, v0, v1
	v_cvt_pk_bf16_f32 v0, v2, v3
	s_waitcnt vmcnt(29)
	v_mov_b32_e32 v2, v9
	s_nop 1
	v_permlane32_swap_b32_e32 v8, v2
	v_permlane32_swap_b32_e32 v4, v5
	v_permlane32_swap_b32_e32 v6, v7
	v_cvt_pk_bf16_f32 v25, v4, v5
	v_cvt_pk_bf16_f32 v1, v6, v7
	v_cvt_pk_bf16_f32 v26, v8, v2
	v_mov_b32_e32 v2, v11
	s_waitcnt vmcnt(28)
	v_mov_b32_e32 v3, v21
	v_permlane32_swap_b32_e32 v10, v2
	s_nop 0
	v_permlane32_swap_b32_e32 v20, v3
	v_cvt_pk_bf16_f32 v2, v10, v2
	v_cvt_pk_bf16_f32 v27, v20, v3
	v_mov_b32_e32 v3, v23
	s_waitcnt vmcnt(27)
	v_mov_b32_e32 v4, v41
	v_mov_b32_e32 v5, v43
	v_permlane32_swap_b32_e32 v22, v3
	v_permlane32_swap_b32_e32 v40, v4
	v_permlane32_swap_b32_e32 v42, v5
	v_cvt_pk_bf16_f32 v3, v22, v3
	v_cvt_pk_bf16_f32 v40, v40, v4
	v_cvt_pk_bf16_f32 v4, v42, v5
	s_waitcnt vmcnt(26)
	v_mov_b32_e32 v5, v49
	s_nop 1
	v_permlane32_swap_b32_e32 v48, v5
	v_cvt_pk_bf16_f32 v41, v48, v5
	v_mov_b32_e32 v5, v51
	s_waitcnt vmcnt(25)
	v_mov_b32_e32 v6, v67
	v_permlane32_swap_b32_e32 v50, v5
	s_nop 0
	v_permlane32_swap_b32_e32 v66, v6
	v_cvt_pk_bf16_f32 v5, v50, v5
	v_cvt_pk_bf16_f32 v42, v66, v6
	v_mov_b32_e32 v6, v69
	s_waitcnt vmcnt(24)
	v_mov_b32_e32 v7, v71
	v_permlane32_swap_b32_e32 v68, v6
	s_nop 0
	v_permlane32_swap_b32_e32 v70, v7
	v_cvt_pk_bf16_f32 v6, v68, v6
	v_cvt_pk_bf16_f32 v43, v70, v7
	v_mov_b32_e32 v7, v73
	s_waitcnt vmcnt(23)
	v_mov_b32_e32 v8, v75
	v_mov_b32_e32 v9, v77
	v_permlane32_swap_b32_e32 v72, v7
	v_permlane32_swap_b32_e32 v74, v8
	v_permlane32_swap_b32_e32 v76, v9
	v_cvt_pk_bf16_f32 v7, v72, v7
	v_cvt_pk_bf16_f32 v66, v74, v8
	v_cvt_pk_bf16_f32 v8, v76, v9
	s_waitcnt vmcnt(22)
	v_mov_b32_e32 v9, v79
	s_nop 1
	v_permlane32_swap_b32_e32 v78, v9
	v_cvt_pk_bf16_f32 v67, v78, v9
	v_mov_b32_e32 v9, v81
	s_waitcnt vmcnt(21)
	v_mov_b32_e32 v10, v83
	v_permlane32_swap_b32_e32 v80, v9
	s_nop 0
	v_permlane32_swap_b32_e32 v82, v10
	v_cvt_pk_bf16_f32 v9, v80, v9
	v_cvt_pk_bf16_f32 v68, v82, v10
	v_mov_b32_e32 v10, v85
	s_waitcnt vmcnt(20)
	v_mov_b32_e32 v11, v87
	v_permlane32_swap_b32_e32 v84, v10
	s_nop 0
	v_permlane32_swap_b32_e32 v86, v11
	v_cvt_pk_bf16_f32 v10, v84, v10
	v_cvt_pk_bf16_f32 v69, v86, v11
	v_mov_b32_e32 v11, v89
	s_waitcnt vmcnt(19)
	v_mov_b32_e32 v20, v91
	v_mov_b32_e32 v21, v93
	v_permlane32_swap_b32_e32 v88, v11
	v_permlane32_swap_b32_e32 v90, v20
	v_permlane32_swap_b32_e32 v92, v21
	v_cvt_pk_bf16_f32 v11, v88, v11
	v_cvt_pk_bf16_f32 v70, v90, v20
	v_cvt_pk_bf16_f32 v20, v92, v21
	s_waitcnt vmcnt(18)
	v_mov_b32_e32 v21, v95
	s_nop 1
	v_permlane32_swap_b32_e32 v94, v21
	v_cvt_pk_bf16_f32 v71, v94, v21
	v_mov_b32_e32 v21, v97
	s_waitcnt vmcnt(17)
	v_mov_b32_e32 v22, v99
	v_permlane32_swap_b32_e32 v96, v21
	s_nop 0
	v_permlane32_swap_b32_e32 v98, v22
	v_cvt_pk_bf16_f32 v21, v96, v21
	v_cvt_pk_bf16_f32 v72, v98, v22
	v_mov_b32_e32 v22, v101
	s_waitcnt vmcnt(16)
	v_mov_b32_e32 v23, v103
	v_permlane32_swap_b32_e32 v100, v22
	s_nop 0
	v_permlane32_swap_b32_e32 v102, v23
	v_cvt_pk_bf16_f32 v22, v100, v22
	v_cvt_pk_bf16_f32 v73, v102, v23
	v_mov_b32_e32 v23, v105
	s_waitcnt vmcnt(15)
	v_mov_b32_e32 v48, v107
	v_mov_b32_e32 v49, v109
	v_permlane32_swap_b32_e32 v104, v23
	v_permlane32_swap_b32_e32 v106, v48
	v_permlane32_swap_b32_e32 v108, v49
	v_cvt_pk_bf16_f32 v23, v104, v23
	v_cvt_pk_bf16_f32 v74, v106, v48
	v_cvt_pk_bf16_f32 v48, v108, v49
	s_waitcnt vmcnt(14)
	v_mov_b32_e32 v49, v111
	s_nop 1
	v_permlane32_swap_b32_e32 v110, v49
	v_cvt_pk_bf16_f32 v75, v110, v49
	v_mov_b32_e32 v49, v113
	s_waitcnt vmcnt(13)
	v_mov_b32_e32 v50, v115
	v_permlane32_swap_b32_e32 v112, v49
	s_nop 0
	v_permlane32_swap_b32_e32 v114, v50
	v_cvt_pk_bf16_f32 v49, v112, v49
	v_cvt_pk_bf16_f32 v76, v114, v50
	v_mov_b32_e32 v50, v117
	s_waitcnt vmcnt(12)
	v_mov_b32_e32 v51, v119
	v_permlane32_swap_b32_e32 v116, v50
	s_nop 0
	v_permlane32_swap_b32_e32 v118, v51
	v_cvt_pk_bf16_f32 v50, v116, v50
	v_cvt_pk_bf16_f32 v77, v118, v51
	v_mov_b32_e32 v51, v121
	s_waitcnt vmcnt(11)
	v_mov_b32_e32 v65, v123
	v_permlane32_swap_b32_e32 v120, v51
	s_nop 0
	v_permlane32_swap_b32_e32 v122, v65
	v_cvt_pk_bf16_f32 v51, v120, v51
	v_mov_b32_e32 v79, v125
	v_cvt_pk_bf16_f32 v78, v122, v65
	s_waitcnt vmcnt(10)
	v_mov_b32_e32 v65, v127
	v_permlane32_swap_b32_e32 v124, v79
	s_nop 0
	v_permlane32_swap_b32_e32 v126, v65
	v_cvt_pk_bf16_f32 v82, v124, v79
	v_cvt_pk_bf16_f32 v79, v126, v65
	v_mov_b32_e32 v65, v129
	s_nop 1
	v_permlane32_swap_b32_e32 v128, v65
	v_cvt_pk_bf16_f32 v83, v128, v65
	s_waitcnt vmcnt(9)
	v_mov_b32_e32 v65, v131
	s_nop 1
	v_permlane32_swap_b32_e32 v130, v65
	v_cvt_pk_bf16_f32 v80, v130, v65
	v_mov_b32_e32 v65, v133
	s_nop 1
	v_permlane32_swap_b32_e32 v132, v65
	v_cvt_pk_bf16_f32 v84, v132, v65
	s_waitcnt vmcnt(8)
	v_mov_b32_e32 v65, v135
	s_nop 1
	v_permlane32_swap_b32_e32 v134, v65
	v_cvt_pk_bf16_f32 v81, v134, v65
	v_mov_b32_e32 v65, v137
	s_nop 1
	v_permlane32_swap_b32_e32 v136, v65
	s_waitcnt vmcnt(7)
	v_mov_b32_e32 v87, v141
	v_cvt_pk_bf16_f32 v85, v136, v65
	v_mov_b32_e32 v65, v139
	s_nop 0
	v_permlane32_swap_b32_e32 v140, v87
	s_waitcnt vmcnt(6)
	v_permlane32_swap_b32_e32 v52, v53
	v_permlane32_swap_b32_e32 v138, v65
	v_cvt_pk_bf16_f32 v86, v138, v65
	v_cvt_pk_bf16_f32 v90, v140, v87
	v_cvt_pk_bf16_f32 v87, v52, v53
	v_mov_b32_e32 v52, v55
	s_waitcnt vmcnt(5)
	v_permlane32_swap_b32_e32 v44, v45
	v_permlane32_swap_b32_e32 v54, v52
	v_cvt_pk_bf16_f32 v91, v54, v52
	v_cvt_pk_bf16_f32 v88, v44, v45
	v_mov_b32_e32 v44, v47
	s_waitcnt vmcnt(4)
	v_permlane32_swap_b32_e32 v36, v37
	v_permlane32_swap_b32_e32 v46, v44
	v_cvt_pk_bf16_f32 v92, v46, v44
	v_cvt_pk_bf16_f32 v89, v36, v37
	v_mov_b32_e32 v36, v39
	s_nop 1
	v_permlane32_swap_b32_e32 v38, v36
	s_waitcnt vmcnt(3)
	v_permlane32_swap_b32_e32 v32, v33
	s_waitcnt vmcnt(2)
	v_permlane32_swap_b32_e32 v28, v29
	v_cvt_pk_bf16_f32 v93, v38, v36
	v_permlane32_swap_b32_e32 v34, v35
	v_cvt_pk_bf16_f32 v32, v32, v33
	v_cvt_pk_bf16_f32 v36, v34, v35
	v_cvt_pk_bf16_f32 v33, v28, v29
	v_mov_b32_e32 v28, v31
	s_waitcnt vmcnt(1)
	v_permlane32_swap_b32_e32 v16, v17
	v_permlane32_swap_b32_e32 v30, v28
	v_cvt_pk_bf16_f32 v37, v30, v28
	v_cvt_pk_bf16_f32 v34, v16, v17
	v_mov_b32_e32 v16, v19
	s_waitcnt vmcnt(0)
	v_permlane32_swap_b32_e32 v12, v13
	v_permlane32_swap_b32_e32 v18, v16
	v_cvt_pk_bf16_f32 v38, v18, v16
	v_cvt_pk_bf16_f32 v35, v12, v13
	v_mov_b32_e32 v12, v15
	s_nop 1
	v_permlane32_swap_b32_e32 v14, v12
	v_or_b32_e32 v30, s16, v61
	v_cvt_pk_bf16_f32 v39, v14, v12
	ds_write_b128 v62, v[24:27] offset:40960
	ds_write_b128 v62, v[40:43] offset:40976
	ds_write_b128 v62, v[66:69] offset:40992
	ds_write_b128 v62, v[70:73] offset:41008
	ds_write_b128 v62, v[74:77] offset:41024
	ds_write_b128 v62, v[78:81] offset:41040
	ds_write_b128 v62, v[86:89] offset:41056
	ds_write_b128 v62, v[32:35] offset:41072
	v_mul_lo_u32 v14, s13, v30
	v_mad_u64_u32 v[12:13], s[16:17], s12, v30, 0
	s_waitcnt lgkmcnt(0)
	v_add3_u32 v13, v13, s4, v14
	v_lshl_add_u64 v[16:17], v[12:13], 1, s[10:11]
	ds_read_b128 v[12:15], v63 offset:40960
	s_lshl_b64 s[16:17], s[14:15], 1
	v_lshl_add_u64 v[16:17], v[16:17], 0, s[16:17]
	v_lshl_add_u64 v[24:25], v[16:17], 0, v[58:59]
	ds_read_b128 v[16:19], v63 offset:42112
	s_waitcnt lgkmcnt(1)
	global_store_dwordx4 v[24:25], v[12:15], off sc1
	s_lshl_b64 s[14:15], s[12:13], 6
	ds_read_b128 v[12:15], v63 offset:43264
	v_lshl_add_u64 v[28:29], v[24:25], 0, s[14:15]
	ds_read_b128 v[24:27], v63 offset:44416
	s_waitcnt lgkmcnt(2)
	global_store_dwordx4 v[28:29], v[16:19], off sc1
	s_nop 1
	v_lshl_add_u64 v[16:17], v[28:29], 0, s[14:15]
	s_waitcnt lgkmcnt(1)
	global_store_dwordx4 v[16:17], v[12:15], off sc1
	v_lshl_add_u64 v[16:17], v[16:17], 0, s[14:15]
	ds_read_b128 v[12:15], v63 offset:45568
	s_waitcnt lgkmcnt(1)
	global_store_dwordx4 v[16:17], v[24:27], off sc1
	s_nop 1
	v_mad_u64_u32 v[24:25], s[18:19], s12, v64, v[16:17]
	s_mul_i32 s18, s13, 0xffffff42
	s_sub_i32 s37, s18, s12
	v_add_u32_e32 v25, s37, v25
	ds_read_b128 v[16:19], v63 offset:46720
	s_waitcnt lgkmcnt(1)
	global_store_dwordx4 v[24:25], v[12:15], off sc1
	ds_read_b128 v[12:15], v63 offset:47872
	v_lshl_add_u64 v[28:29], v[24:25], 0, s[14:15]
	ds_read_b128 v[24:27], v63 offset:49024
	s_waitcnt lgkmcnt(2)
	global_store_dwordx4 v[28:29], v[16:19], off sc1
	s_cmp_lg_u32 s1, s36
	s_nop 0
	v_lshl_add_u64 v[16:17], v[28:29], 0, s[14:15]
	s_waitcnt lgkmcnt(1)
	global_store_dwordx4 v[16:17], v[12:15], off sc1
	s_nop 1
	v_lshl_add_u64 v[12:13], v[16:17], 0, s[14:15]
	s_waitcnt lgkmcnt(0)
	global_store_dwordx4 v[12:13], v[24:27], off sc1
	s_waitcnt lgkmcnt(0)
	ds_write_b128 v62, v[0:3] offset:40960
	ds_write_b128 v62, v[4:7] offset:40976
	ds_write_b128 v62, v[8:11] offset:40992
	ds_write_b128 v62, v[20:23] offset:41008
	ds_write_b128 v62, v[48:51] offset:41024
	ds_write_b128 v62, v[82:85] offset:41040
	ds_write_b128 v62, v[90:93] offset:41056
	ds_write_b128 v62, v[36:39] offset:41072
	v_or_b32_e32 v0, 2, v30
	s_waitcnt lgkmcnt(0)
	v_mul_lo_u32 v1, s13, v0
	v_mad_u64_u32 v[4:5], s[18:19], s12, v0, 0
	v_add3_u32 v5, v5, s4, v1
	ds_read_b128 v[0:3], v63 offset:40960
	v_lshl_add_u64 v[4:5], v[4:5], 1, s[10:11]
	v_lshl_add_u64 v[4:5], v[4:5], 0, s[16:17]
	v_lshl_add_u64 v[8:9], v[4:5], 0, v[58:59]
	ds_read_b128 v[4:7], v63 offset:42112
	s_waitcnt lgkmcnt(1)
	global_store_dwordx4 v[8:9], v[0:3], off sc1
	ds_read_b128 v[0:3], v63 offset:43264
	v_lshl_add_u64 v[12:13], v[8:9], 0, s[14:15]
	ds_read_b128 v[8:11], v63 offset:44416
	s_waitcnt lgkmcnt(2)
	global_store_dwordx4 v[12:13], v[4:7], off sc1
	s_nop 1
	v_lshl_add_u64 v[4:5], v[12:13], 0, s[14:15]
	s_waitcnt lgkmcnt(1)
	global_store_dwordx4 v[4:5], v[0:3], off sc1
	ds_read_b128 v[0:3], v63 offset:45568
	v_lshl_add_u64 v[4:5], v[4:5], 0, s[14:15]
	s_waitcnt lgkmcnt(1)
	global_store_dwordx4 v[4:5], v[8:11], off sc1
	s_nop 1
	v_mad_u64_u32 v[8:9], s[10:11], s12, v64, v[4:5]
	v_add_u32_e32 v9, s37, v9
	ds_read_b128 v[4:7], v63 offset:46720
	s_waitcnt lgkmcnt(1)
	global_store_dwordx4 v[8:9], v[0:3], off sc1
	ds_read_b128 v[0:3], v63 offset:47872
	v_lshl_add_u64 v[12:13], v[8:9], 0, s[14:15]
	ds_read_b128 v[8:11], v63 offset:49024
	s_waitcnt lgkmcnt(2)
	global_store_dwordx4 v[12:13], v[4:7], off sc1
	s_nop 1
	v_lshl_add_u64 v[4:5], v[12:13], 0, s[14:15]
	s_waitcnt lgkmcnt(1)
	global_store_dwordx4 v[4:5], v[0:3], off sc1
	s_nop 1
	v_lshl_add_u64 v[0:1], v[4:5], 0, s[14:15]
	s_waitcnt lgkmcnt(0)
	global_store_dwordx4 v[0:1], v[8:11], off sc1
	s_waitcnt lgkmcnt(0)
	s_cbranch_scc0 .LBB0_93

.LBB0_267:
	s_add_i32 s4, s77, s43
	v_add_u32_e32 v62, s4, v152
	v_mad_u64_u32 v[54:55], s[4:5], v62, s20, 0
	v_ashrrev_i32_e32 v57, 31, v62
	v_mov_b32_e32 v56, v55
	v_mad_u64_u32 v[56:57], s[4:5], v57, s20, v[56:57]
	v_mov_b32_e32 v55, v56
	v_lshl_add_u64 v[56:57], v[54:55], 1, s[56:57]
	v_lshlrev_b64 v[54:55], 1, v[158:159]
	v_lshl_add_u64 v[60:61], v[56:57], 0, v[54:55]
	v_cvt_pk_bf16_f32 v56, v146, v147
	v_cvt_pk_bf16_f32 v57, v148, v149
	v_cvt_pk_bf16_f32 v58, v142, v143
	v_cvt_pk_bf16_f32 v59, v144, v145
	global_store_dwordx4 v[60:61], v[56:59], off sc1
	s_nop 1
	v_cvt_pk_bf16_f32 v56, v138, v139
	v_cvt_pk_bf16_f32 v57, v140, v141
	v_cvt_pk_bf16_f32 v58, v134, v135
	v_cvt_pk_bf16_f32 v59, v136, v137
	global_store_dwordx4 v[60:61], v[56:59], off offset:256 sc1
	s_nop 1
	v_add_u32_e32 v56, 16, v62
	v_ashrrev_i32_e32 v59, 31, v56
	v_mad_u64_u32 v[56:57], s[4:5], v56, s20, 0
	v_mov_b32_e32 v58, v57
	v_mad_u64_u32 v[58:59], s[4:5], v59, s20, v[58:59]
	v_mov_b32_e32 v57, v58
	v_lshl_add_u64 v[56:57], v[56:57], 1, s[56:57]
	v_lshl_add_u64 v[60:61], v[56:57], 0, v[54:55]
	v_cvt_pk_bf16_f32 v56, v130, v131
	v_cvt_pk_bf16_f32 v57, v132, v133
	v_cvt_pk_bf16_f32 v58, v126, v127
	v_cvt_pk_bf16_f32 v59, v128, v129
	global_store_dwordx4 v[60:61], v[56:59], off sc1
	s_nop 1
	v_cvt_pk_bf16_f32 v56, v122, v123
	v_cvt_pk_bf16_f32 v57, v124, v125
	v_cvt_pk_bf16_f32 v58, v118, v119
	v_cvt_pk_bf16_f32 v59, v120, v121
	global_store_dwordx4 v[60:61], v[56:59], off offset:256 sc1
	s_nop 1
	v_add_u32_e32 v56, 32, v62
	v_ashrrev_i32_e32 v59, 31, v56
	v_mad_u64_u32 v[56:57], s[4:5], v56, s20, 0
	v_mov_b32_e32 v58, v57
	v_mad_u64_u32 v[58:59], s[4:5], v59, s20, v[58:59]
	v_mov_b32_e32 v57, v58
	v_lshl_add_u64 v[56:57], v[56:57], 1, s[56:57]
	v_lshl_add_u64 v[60:61], v[56:57], 0, v[54:55]
	v_cvt_pk_bf16_f32 v56, v114, v115
	v_cvt_pk_bf16_f32 v57, v116, v117
	v_cvt_pk_bf16_f32 v58, v110, v111
	v_cvt_pk_bf16_f32 v59, v112, v113
	global_store_dwordx4 v[60:61], v[56:59], off sc1
	s_nop 1
	v_cvt_pk_bf16_f32 v56, v106, v107
	v_cvt_pk_bf16_f32 v57, v108, v109
	v_cvt_pk_bf16_f32 v58, v102, v103
	v_cvt_pk_bf16_f32 v59, v104, v105
	global_store_dwordx4 v[60:61], v[56:59], off offset:256 sc1
	s_nop 1
	v_add_u32_e32 v56, 48, v62
	v_ashrrev_i32_e32 v59, 31, v56
	v_mad_u64_u32 v[56:57], s[4:5], v56, s20, 0
	v_mov_b32_e32 v58, v57
	v_mad_u64_u32 v[58:59], s[4:5], v59, s20, v[58:59]
	v_mov_b32_e32 v57, v58
	v_lshl_add_u64 v[56:57], v[56:57], 1, s[56:57]
	v_lshl_add_u64 v[60:61], v[56:57], 0, v[54:55]
	v_cvt_pk_bf16_f32 v56, v98, v99
	v_cvt_pk_bf16_f32 v57, v100, v101
	v_cvt_pk_bf16_f32 v58, v94, v95
	v_cvt_pk_bf16_f32 v59, v96, v97
	global_store_dwordx4 v[60:61], v[56:59], off sc1
	s_nop 1
	v_cvt_pk_bf16_f32 v56, v90, v91
	v_cvt_pk_bf16_f32 v57, v92, v93
	v_cvt_pk_bf16_f32 v58, v86, v87
	v_cvt_pk_bf16_f32 v59, v88, v89
	global_store_dwordx4 v[60:61], v[56:59], off offset:256 sc1
	s_nop 1
	v_add_u32_e32 v56, 0x80, v62
	v_ashrrev_i32_e32 v59, 31, v56
	v_mad_u64_u32 v[56:57], s[4:5], v56, s20, 0
	v_mov_b32_e32 v58, v57
	v_mad_u64_u32 v[58:59], s[4:5], v59, s20, v[58:59]
	v_mov_b32_e32 v57, v58
	v_lshl_add_u64 v[56:57], v[56:57], 1, s[56:57]
	v_lshl_add_u64 v[60:61], v[56:57], 0, v[54:55]
	v_cvt_pk_bf16_f32 v56, v82, v83
	v_cvt_pk_bf16_f32 v57, v84, v85
	v_cvt_pk_bf16_f32 v58, v78, v79
	v_cvt_pk_bf16_f32 v59, v80, v81
	global_store_dwordx4 v[60:61], v[56:59], off sc1
	s_nop 1
	v_cvt_pk_bf16_f32 v56, v74, v75
	v_cvt_pk_bf16_f32 v57, v76, v77
	v_cvt_pk_bf16_f32 v58, v70, v71
	v_cvt_pk_bf16_f32 v59, v72, v73
	global_store_dwordx4 v[60:61], v[56:59], off offset:256 sc1
	s_nop 1
	v_add_u32_e32 v56, 0x90, v62
	v_ashrrev_i32_e32 v59, 31, v56
	v_mad_u64_u32 v[56:57], s[4:5], v56, s20, 0
	v_mov_b32_e32 v58, v57
	v_mad_u64_u32 v[58:59], s[4:5], v59, s20, v[58:59]
	v_mov_b32_e32 v57, v58
	v_lshl_add_u64 v[56:57], v[56:57], 1, s[56:57]
	v_lshl_add_u64 v[60:61], v[56:57], 0, v[54:55]
	v_cvt_pk_bf16_f32 v56, v50, v51
	v_cvt_pk_bf16_f32 v57, v52, v53
	v_cvt_pk_bf16_f32 v58, v46, v47
	v_cvt_pk_bf16_f32 v59, v48, v49
	global_store_dwordx4 v[60:61], v[56:59], off sc1
	s_nop 1
	v_cvt_pk_bf16_f32 v56, v42, v43
	v_cvt_pk_bf16_f32 v57, v44, v45
	v_cvt_pk_bf16_f32 v58, v38, v39
	v_cvt_pk_bf16_f32 v59, v40, v41
	global_store_dwordx4 v[60:61], v[56:59], off offset:256 sc1
	s_nop 1
	v_add_u32_e32 v56, 0xa0, v62
	v_ashrrev_i32_e32 v59, 31, v56
	v_mad_u64_u32 v[56:57], s[4:5], v56, s20, 0
	v_mov_b32_e32 v58, v57
	v_mad_u64_u32 v[58:59], s[4:5], v59, s20, v[58:59]
	v_mov_b32_e32 v57, v58
	v_lshl_add_u64 v[56:57], v[56:57], 1, s[56:57]
	v_lshl_add_u64 v[60:61], v[56:57], 0, v[54:55]
	v_cvt_pk_bf16_f32 v56, v34, v35
	v_cvt_pk_bf16_f32 v57, v36, v37
	v_cvt_pk_bf16_f32 v58, v30, v31
	v_cvt_pk_bf16_f32 v59, v32, v33
	global_store_dwordx4 v[60:61], v[56:59], off sc1
	s_nop 1
	v_cvt_pk_bf16_f32 v56, v26, v27
	v_cvt_pk_bf16_f32 v57, v28, v29
	v_cvt_pk_bf16_f32 v58, v22, v23
	v_cvt_pk_bf16_f32 v59, v24, v25
	global_store_dwordx4 v[60:61], v[56:59], off offset:256 sc1
	s_nop 1
	v_add_u32_e32 v56, 0xb0, v62
	v_ashrrev_i32_e32 v59, 31, v56
	v_mad_u64_u32 v[56:57], s[4:5], v56, s20, 0
	v_mov_b32_e32 v58, v57
	v_mad_u64_u32 v[58:59], s[4:5], v59, s20, v[58:59]
	v_mov_b32_e32 v57, v58
	v_lshl_add_u64 v[56:57], v[56:57], 1, s[56:57]
	v_lshl_add_u64 v[58:59], v[56:57], 0, v[54:55]
	v_cvt_pk_bf16_f32 v54, v18, v19
	v_cvt_pk_bf16_f32 v55, v20, v21
	v_cvt_pk_bf16_f32 v56, v10, v11
	v_cvt_pk_bf16_f32 v57, v12, v13
	global_store_dwordx4 v[58:59], v[54:57], off sc1
	s_nop 1
	v_cvt_pk_bf16_f32 v54, v6, v7
	v_cvt_pk_bf16_f32 v55, v8, v9
	v_cvt_pk_bf16_f32 v56, v2, v3
	v_cvt_pk_bf16_f32 v57, v4, v5
	global_store_dwordx4 v[58:59], v[54:57], off offset:256 sc1
	s_cbranch_execnz .LBB0_266

.LBB0_305:
	v_mad_u64_u32 v[142:143], s[8:9], v168, s20, 0
	v_mov_b32_e32 v0, v143
	v_mad_u64_u32 v[168:169], s[8:9], v169, s20, v[0:1]
	v_mov_b32_e32 v143, v168
	v_cvt_pk_bf16_f32 v168, v148, v149
	v_cvt_pk_bf16_f32 v169, v146, v147
	v_cvt_pk_bf16_f32 v170, v170, v171
	v_cvt_pk_bf16_f32 v171, v144, v145
	v_lshrrev_b32_e32 v144, 2, v175
	v_add_u32_e32 v144, 0x1a300, v144
	ds_read_b32 v144, v144 offset:4
	v_lshl_add_u64 v[142:143], v[142:143], 1, s[56:57]
	v_lshl_add_u64 v[142:143], v[158:159], 1, v[142:143]
	global_store_dwordx4 v[142:143], v[168:171], off sc1
	s_waitcnt lgkmcnt(0)
	v_mov_b32_e32 v0, v144
	v_pk_mul_f32 v[144:145], v[138:139], v[0:1] op_sel_hi:[1,0]
	v_pk_mul_f32 v[138:139], v[140:141], v[0:1] op_sel_hi:[1,0]
	v_pk_mul_f32 v[140:141], v[58:59], v[144:145]
	v_pk_mul_f32 v[144:145], v[134:135], v[0:1] op_sel_hi:[1,0]
	v_pk_mul_f32 v[134:135], v[136:137], v[0:1] op_sel_hi:[1,0]
	v_pk_mul_f32 v[138:139], v[60:61], v[138:139]
	v_pk_mul_f32 v[134:135], v[56:57], v[134:135]
	v_pk_mul_f32 v[136:137], v[54:55], v[144:145]
	s_and_b64 vcc, exec, s[6:7]
	s_cbranch_vccnz .LBB0_307
	ds_bpermute_b32 v144, v172, v140
	ds_bpermute_b32 v145, v172, v141
	ds_bpermute_b32 v146, v172, v136
	ds_bpermute_b32 v148, v172, v138
	ds_bpermute_b32 v149, v172, v139
	ds_bpermute_b32 v147, v172, v137
	ds_bpermute_b32 v168, v172, v134
	ds_bpermute_b32 v169, v172, v135
	s_waitcnt lgkmcnt(6)
	v_pk_mul_f32 v[144:145], v[164:165], v[144:145]
	s_waitcnt lgkmcnt(3)
	v_pk_mul_f32 v[148:149], v[166:167], v[148:149]
	v_pk_fma_f32 v[140:141], v[154:155], v[140:141], v[144:145]
	s_waitcnt lgkmcnt(2)
	v_pk_mul_f32 v[144:145], v[162:163], v[146:147]
	s_waitcnt lgkmcnt(0)
	v_pk_mul_f32 v[146:147], v[160:161], v[168:169]
	v_pk_fma_f32 v[138:139], v[156:157], v[138:139], v[148:149]
	v_pk_fma_f32 v[134:135], v[152:153], v[134:135], v[146:147]
	v_pk_fma_f32 v[136:137], v[150:151], v[136:137], v[144:145]
.LBB0_307:
	v_add_u32_e32 v152, 16, v173
	v_add_u32_e32 v150, s77, v152
	s_and_b64 vcc, exec, s[6:7]
	v_ashrrev_i32_e32 v151, 31, v150
	v_cvt_pk_bf16_f32 v144, v140, v141
	v_cvt_pk_bf16_f32 v145, v138, v139
	v_cvt_pk_bf16_f32 v146, v136, v137
	v_cvt_pk_bf16_f32 v147, v134, v135
	global_store_dwordx4 v[142:143], v[144:147], off offset:256 sc1
	s_cbranch_vccz .LBB0_309
	s_nop 0
	v_mov_b32_e32 v146, 0
	v_mov_b32_e32 v138, 1.0
	v_mov_b32_e32 v139, v138
	v_mov_b32_e32 v140, v138
	v_mov_b32_e32 v141, v138
	v_mov_b32_e32 v134, v138
	v_mov_b32_e32 v135, v138
	v_mov_b32_e32 v136, v138
	v_mov_b32_e32 v137, v138
	v_mov_b32_e32 v147, v146
	v_mov_b32_e32 v148, v146
	v_mov_b32_e32 v149, v146
	v_mov_b32_e32 v144, v146
	v_mov_b32_e32 v145, v146
	v_mov_b32_e32 v142, v146
	v_mov_b32_e32 v143, v146
	s_branch .LBB0_310

.LBB0_312:
	v_mad_u64_u32 v[126:127], s[8:9], v150, s20, 0
	v_mov_b32_e32 v150, v127
	v_mad_u64_u32 v[150:151], s[8:9], v151, s20, v[150:151]
	v_add_u32_e32 v0, s33, v0
	v_mov_b32_e32 v127, v150
	v_cvt_pk_bf16_f32 v150, v132, v133
	v_cvt_pk_bf16_f32 v151, v130, v131
	v_cvt_pk_bf16_f32 v152, v152, v153
	v_cvt_pk_bf16_f32 v153, v128, v129
	v_lshrrev_b32_e32 v128, 2, v0
	v_add_u32_e32 v128, 0x1a300, v128
	ds_read_b32 v128, v128 offset:4
	v_lshl_add_u64 v[126:127], v[126:127], 1, s[56:57]
	v_lshl_add_u64 v[126:127], v[158:159], 1, v[126:127]
	global_store_dwordx4 v[126:127], v[150:153], off sc1
	s_waitcnt lgkmcnt(0)
	v_mov_b32_e32 v0, v128
	v_pk_mul_f32 v[128:129], v[122:123], v[0:1] op_sel_hi:[1,0]
	v_pk_mul_f32 v[122:123], v[124:125], v[0:1] op_sel_hi:[1,0]
	v_pk_mul_f32 v[124:125], v[58:59], v[128:129]
	v_pk_mul_f32 v[128:129], v[118:119], v[0:1] op_sel_hi:[1,0]
	v_pk_mul_f32 v[118:119], v[120:121], v[0:1] op_sel_hi:[1,0]
	v_pk_mul_f32 v[122:123], v[60:61], v[122:123]
	v_pk_mul_f32 v[118:119], v[56:57], v[118:119]
	v_pk_mul_f32 v[120:121], v[54:55], v[128:129]
	s_and_b64 vcc, exec, s[6:7]
	s_cbranch_vccnz .LBB0_314
	ds_bpermute_b32 v128, v172, v124
	ds_bpermute_b32 v129, v172, v125
	ds_bpermute_b32 v130, v172, v120
	ds_bpermute_b32 v132, v172, v122
	ds_bpermute_b32 v133, v172, v123
	ds_bpermute_b32 v131, v172, v121
	ds_bpermute_b32 v150, v172, v118
	ds_bpermute_b32 v151, v172, v119
	s_waitcnt lgkmcnt(6)
	v_pk_mul_f32 v[128:129], v[146:147], v[128:129]
	s_waitcnt lgkmcnt(3)
	v_pk_mul_f32 v[132:133], v[148:149], v[132:133]
	s_waitcnt vmcnt(2)
	v_pk_fma_f32 v[124:125], v[138:139], v[124:125], v[128:129]
	s_waitcnt lgkmcnt(2)
	v_pk_mul_f32 v[128:129], v[144:145], v[130:131]
	s_waitcnt lgkmcnt(0)
	v_pk_mul_f32 v[130:131], v[142:143], v[150:151]
	v_pk_fma_f32 v[122:123], v[140:141], v[122:123], v[132:133]
	s_waitcnt vmcnt(1)
	v_pk_fma_f32 v[118:119], v[136:137], v[118:119], v[130:131]
	v_pk_fma_f32 v[120:121], v[134:135], v[120:121], v[128:129]
.LBB0_314:
	v_cvt_pk_bf16_f32 v128, v124, v125
	v_cvt_pk_bf16_f32 v129, v122, v123
	s_nop 0
	v_cvt_pk_bf16_f32 v130, v120, v121
	v_cvt_pk_bf16_f32 v131, v118, v119
	global_store_dwordx4 v[126:127], v[128:131], off offset:256 sc1
	s_waitcnt vmcnt(2)
	v_add_u32_e32 v136, 32, v173
	v_add_u32_e32 v134, s77, v136
	s_and_b64 vcc, exec, s[6:7]
	v_ashrrev_i32_e32 v135, 31, v134
	s_cbranch_vccz .LBB0_316
	v_mov_b32_e32 v130, 0
	v_mov_b32_e32 v122, 1.0
	v_mov_b32_e32 v123, v122
	v_mov_b32_e32 v124, v122
	v_mov_b32_e32 v125, v122
	v_mov_b32_e32 v118, v122
	v_mov_b32_e32 v119, v122
	v_mov_b32_e32 v120, v122
	v_mov_b32_e32 v121, v122
	v_mov_b32_e32 v131, v130
	v_mov_b32_e32 v132, v130
	v_mov_b32_e32 v133, v130
	v_mov_b32_e32 v128, v130
	v_mov_b32_e32 v129, v130
	v_mov_b32_e32 v126, v130
	v_mov_b32_e32 v127, v130
	s_branch .LBB0_317

.LBB0_319:
	v_mad_u64_u32 v[110:111], s[8:9], v134, s20, 0
	v_mov_b32_e32 v134, v111
	v_mad_u64_u32 v[134:135], s[8:9], v135, s20, v[134:135]
	v_add_u32_e32 v0, s33, v0
	v_mov_b32_e32 v111, v134
	v_cvt_pk_bf16_f32 v134, v116, v117
	v_cvt_pk_bf16_f32 v135, v114, v115
	v_cvt_pk_bf16_f32 v136, v136, v137
	v_cvt_pk_bf16_f32 v137, v112, v113
	v_lshrrev_b32_e32 v112, 2, v0
	v_add_u32_e32 v112, 0x1a300, v112
	ds_read_b32 v112, v112 offset:4
	v_lshl_add_u64 v[110:111], v[110:111], 1, s[56:57]
	v_lshl_add_u64 v[110:111], v[158:159], 1, v[110:111]
	global_store_dwordx4 v[110:111], v[134:137], off sc1
	s_waitcnt lgkmcnt(0)
	v_mov_b32_e32 v0, v112
	v_pk_mul_f32 v[112:113], v[106:107], v[0:1] op_sel_hi:[1,0]
	v_pk_mul_f32 v[106:107], v[108:109], v[0:1] op_sel_hi:[1,0]
	v_pk_mul_f32 v[108:109], v[58:59], v[112:113]
	v_pk_mul_f32 v[112:113], v[102:103], v[0:1] op_sel_hi:[1,0]
	v_pk_mul_f32 v[102:103], v[104:105], v[0:1] op_sel_hi:[1,0]
	v_pk_mul_f32 v[106:107], v[60:61], v[106:107]
	v_pk_mul_f32 v[102:103], v[56:57], v[102:103]
	v_pk_mul_f32 v[104:105], v[54:55], v[112:113]
	s_and_b64 vcc, exec, s[6:7]
	s_cbranch_vccnz .LBB0_321
	ds_bpermute_b32 v112, v172, v108
	ds_bpermute_b32 v113, v172, v109
	ds_bpermute_b32 v114, v172, v104
	ds_bpermute_b32 v116, v172, v106
	ds_bpermute_b32 v117, v172, v107
	ds_bpermute_b32 v115, v172, v105
	ds_bpermute_b32 v134, v172, v102
	ds_bpermute_b32 v135, v172, v103
	s_waitcnt lgkmcnt(6)
	v_pk_mul_f32 v[112:113], v[130:131], v[112:113]
	s_waitcnt lgkmcnt(3)
	v_pk_mul_f32 v[116:117], v[132:133], v[116:117]
	s_waitcnt vmcnt(2)
	v_pk_fma_f32 v[108:109], v[122:123], v[108:109], v[112:113]
	s_waitcnt lgkmcnt(2)
	v_pk_mul_f32 v[112:113], v[128:129], v[114:115]
	s_waitcnt lgkmcnt(0)
	v_pk_mul_f32 v[114:115], v[126:127], v[134:135]
	v_pk_fma_f32 v[106:107], v[124:125], v[106:107], v[116:117]
	s_waitcnt vmcnt(1)
	v_pk_fma_f32 v[102:103], v[120:121], v[102:103], v[114:115]
	v_pk_fma_f32 v[104:105], v[118:119], v[104:105], v[112:113]
.LBB0_321:
	s_waitcnt vmcnt(1)
	v_add_u32_e32 v120, 48, v173
	v_add_u32_e32 v118, s77, v120
	s_and_b64 vcc, exec, s[6:7]
	v_ashrrev_i32_e32 v119, 31, v118
	v_cvt_pk_bf16_f32 v112, v108, v109
	v_cvt_pk_bf16_f32 v113, v106, v107
	v_cvt_pk_bf16_f32 v114, v104, v105
	v_cvt_pk_bf16_f32 v115, v102, v103
	global_store_dwordx4 v[110:111], v[112:115], off offset:256 sc1
	s_cbranch_vccz .LBB0_323
	s_nop 0
	v_mov_b32_e32 v114, 0
	v_mov_b32_e32 v106, 1.0
	v_mov_b32_e32 v107, v106
	v_mov_b32_e32 v108, v106
	v_mov_b32_e32 v109, v106
	v_mov_b32_e32 v102, v106
	v_mov_b32_e32 v103, v106
	v_mov_b32_e32 v104, v106
	v_mov_b32_e32 v105, v106
	v_mov_b32_e32 v115, v114
	v_mov_b32_e32 v116, v114
	v_mov_b32_e32 v117, v114
	v_mov_b32_e32 v112, v114
	v_mov_b32_e32 v113, v114
	v_mov_b32_e32 v110, v114
	v_mov_b32_e32 v111, v114
	s_branch .LBB0_324

.LBB0_326:
	v_mad_u64_u32 v[94:95], s[8:9], v118, s20, 0
	v_mov_b32_e32 v118, v95
	v_mad_u64_u32 v[118:119], s[8:9], v119, s20, v[118:119]
	v_add_u32_e32 v0, s33, v0
	v_mov_b32_e32 v95, v118
	v_cvt_pk_bf16_f32 v118, v100, v101
	v_cvt_pk_bf16_f32 v119, v98, v99
	v_cvt_pk_bf16_f32 v120, v120, v121
	v_cvt_pk_bf16_f32 v121, v96, v97
	v_lshrrev_b32_e32 v96, 2, v0
	v_add_u32_e32 v96, 0x1a300, v96
	ds_read_b32 v96, v96 offset:4
	v_lshl_add_u64 v[94:95], v[94:95], 1, s[56:57]
	v_lshl_add_u64 v[94:95], v[158:159], 1, v[94:95]
	global_store_dwordx4 v[94:95], v[118:121], off sc1
	s_waitcnt lgkmcnt(0)
	v_mov_b32_e32 v0, v96
	v_pk_mul_f32 v[96:97], v[90:91], v[0:1] op_sel_hi:[1,0]
	v_pk_mul_f32 v[90:91], v[92:93], v[0:1] op_sel_hi:[1,0]
	v_pk_mul_f32 v[92:93], v[58:59], v[96:97]
	v_pk_mul_f32 v[96:97], v[86:87], v[0:1] op_sel_hi:[1,0]
	v_pk_mul_f32 v[86:87], v[88:89], v[0:1] op_sel_hi:[1,0]
	v_pk_mul_f32 v[90:91], v[60:61], v[90:91]
	v_pk_mul_f32 v[86:87], v[56:57], v[86:87]
	v_pk_mul_f32 v[88:89], v[54:55], v[96:97]
	s_and_b64 vcc, exec, s[6:7]
	s_cbranch_vccnz .LBB0_328
	ds_bpermute_b32 v96, v172, v92
	ds_bpermute_b32 v97, v172, v93
	ds_bpermute_b32 v98, v172, v88
	ds_bpermute_b32 v100, v172, v90
	ds_bpermute_b32 v101, v172, v91
	ds_bpermute_b32 v99, v172, v89
	ds_bpermute_b32 v118, v172, v86
	ds_bpermute_b32 v119, v172, v87
	s_waitcnt lgkmcnt(6)
	v_pk_mul_f32 v[96:97], v[114:115], v[96:97]
	s_waitcnt lgkmcnt(3)
	v_pk_mul_f32 v[100:101], v[116:117], v[100:101]
	s_waitcnt vmcnt(2)
	v_pk_fma_f32 v[92:93], v[106:107], v[92:93], v[96:97]
	s_waitcnt lgkmcnt(2)
	v_pk_mul_f32 v[96:97], v[112:113], v[98:99]
	s_waitcnt lgkmcnt(0)
	v_pk_mul_f32 v[98:99], v[110:111], v[118:119]
	v_pk_fma_f32 v[90:91], v[108:109], v[90:91], v[100:101]
	s_waitcnt vmcnt(1)
	v_pk_fma_f32 v[86:87], v[104:105], v[86:87], v[98:99]
	v_pk_fma_f32 v[88:89], v[102:103], v[88:89], v[96:97]
.LBB0_328:
	v_cvt_pk_bf16_f32 v96, v92, v93
	v_cvt_pk_bf16_f32 v97, v90, v91
	s_nop 0
	v_cvt_pk_bf16_f32 v98, v88, v89
	v_cvt_pk_bf16_f32 v99, v86, v87
	global_store_dwordx4 v[94:95], v[96:99], off offset:256 sc1
	s_waitcnt vmcnt(2)
	v_add_u32_e32 v104, 0x80, v173
	v_add_u32_e32 v102, s77, v104
	s_and_b64 vcc, exec, s[6:7]
	v_ashrrev_i32_e32 v103, 31, v102
	s_cbranch_vccz .LBB0_330
	v_mov_b32_e32 v98, 0
	v_mov_b32_e32 v90, 1.0
	v_mov_b32_e32 v91, v90
	v_mov_b32_e32 v92, v90
	v_mov_b32_e32 v93, v90
	v_mov_b32_e32 v86, v90
	v_mov_b32_e32 v87, v90
	v_mov_b32_e32 v88, v90
	v_mov_b32_e32 v89, v90
	v_mov_b32_e32 v99, v98
	v_mov_b32_e32 v100, v98
	v_mov_b32_e32 v101, v98
	v_mov_b32_e32 v96, v98
	v_mov_b32_e32 v97, v98
	v_mov_b32_e32 v94, v98
	v_mov_b32_e32 v95, v98
	s_branch .LBB0_331

.LBB0_333:
	v_mad_u64_u32 v[78:79], s[8:9], v102, s20, 0
	v_mov_b32_e32 v102, v79
	v_mad_u64_u32 v[102:103], s[8:9], v103, s20, v[102:103]
	v_add_u32_e32 v0, s33, v0
	v_mov_b32_e32 v79, v102
	v_cvt_pk_bf16_f32 v102, v84, v85
	v_cvt_pk_bf16_f32 v103, v82, v83
	v_cvt_pk_bf16_f32 v104, v104, v105
	v_cvt_pk_bf16_f32 v105, v80, v81
	v_lshrrev_b32_e32 v80, 2, v0
	v_add_u32_e32 v80, 0x1a300, v80
	ds_read_b32 v80, v80 offset:4
	v_lshl_add_u64 v[78:79], v[78:79], 1, s[56:57]
	v_lshl_add_u64 v[78:79], v[158:159], 1, v[78:79]
	global_store_dwordx4 v[78:79], v[102:105], off sc1
	s_waitcnt lgkmcnt(0)
	v_mov_b32_e32 v0, v80
	v_pk_mul_f32 v[80:81], v[74:75], v[0:1] op_sel_hi:[1,0]
	v_pk_mul_f32 v[74:75], v[76:77], v[0:1] op_sel_hi:[1,0]
	v_pk_mul_f32 v[76:77], v[58:59], v[80:81]
	v_pk_mul_f32 v[80:81], v[70:71], v[0:1] op_sel_hi:[1,0]
	v_pk_mul_f32 v[70:71], v[72:73], v[0:1] op_sel_hi:[1,0]
	v_pk_mul_f32 v[74:75], v[60:61], v[74:75]
	v_pk_mul_f32 v[70:71], v[56:57], v[70:71]
	v_pk_mul_f32 v[72:73], v[54:55], v[80:81]
	s_and_b64 vcc, exec, s[6:7]
	s_cbranch_vccnz .LBB0_335
	ds_bpermute_b32 v80, v172, v76
	ds_bpermute_b32 v81, v172, v77
	ds_bpermute_b32 v82, v172, v72
	ds_bpermute_b32 v84, v172, v74
	ds_bpermute_b32 v85, v172, v75
	ds_bpermute_b32 v83, v172, v73
	ds_bpermute_b32 v102, v172, v70
	ds_bpermute_b32 v103, v172, v71
	s_waitcnt lgkmcnt(6)
	v_pk_mul_f32 v[80:81], v[98:99], v[80:81]
	s_waitcnt lgkmcnt(3)
	v_pk_mul_f32 v[84:85], v[100:101], v[84:85]
	s_waitcnt vmcnt(2)
	v_pk_fma_f32 v[76:77], v[90:91], v[76:77], v[80:81]
	s_waitcnt lgkmcnt(2)
	v_pk_mul_f32 v[80:81], v[96:97], v[82:83]
	s_waitcnt lgkmcnt(0)
	v_pk_mul_f32 v[82:83], v[94:95], v[102:103]
	v_pk_fma_f32 v[74:75], v[92:93], v[74:75], v[84:85]
	s_waitcnt vmcnt(1)
	v_pk_fma_f32 v[70:71], v[88:89], v[70:71], v[82:83]
	v_pk_fma_f32 v[72:73], v[86:87], v[72:73], v[80:81]
.LBB0_335:
	s_waitcnt vmcnt(1)
	v_add_u32_e32 v88, 0x90, v173
	v_add_u32_e32 v86, s77, v88
	s_and_b64 vcc, exec, s[6:7]
	v_ashrrev_i32_e32 v87, 31, v86
	v_cvt_pk_bf16_f32 v80, v76, v77
	v_cvt_pk_bf16_f32 v81, v74, v75
	v_cvt_pk_bf16_f32 v82, v72, v73
	v_cvt_pk_bf16_f32 v83, v70, v71
	global_store_dwordx4 v[78:79], v[80:83], off offset:256 sc1
	s_cbranch_vccz .LBB0_337
	s_nop 0
	v_mov_b32_e32 v82, 0
	v_mov_b32_e32 v74, 1.0
	v_mov_b32_e32 v75, v74
	v_mov_b32_e32 v76, v74
	v_mov_b32_e32 v77, v74
	v_mov_b32_e32 v70, v74
	v_mov_b32_e32 v71, v74
	v_mov_b32_e32 v72, v74
	v_mov_b32_e32 v73, v74
	v_mov_b32_e32 v83, v82
	v_mov_b32_e32 v84, v82
	v_mov_b32_e32 v85, v82
	v_mov_b32_e32 v80, v82
	v_mov_b32_e32 v81, v82
	v_mov_b32_e32 v78, v82
	v_mov_b32_e32 v79, v82
	s_branch .LBB0_338

.LBB0_340:
	v_mad_u64_u32 v[46:47], s[8:9], v86, s20, 0
	v_mov_b32_e32 v86, v47
	v_mad_u64_u32 v[86:87], s[8:9], v87, s20, v[86:87]
	v_add_u32_e32 v0, s33, v0
	v_mov_b32_e32 v47, v86
	v_cvt_pk_bf16_f32 v86, v52, v53
	v_cvt_pk_bf16_f32 v87, v50, v51
	v_cvt_pk_bf16_f32 v88, v88, v89
	v_cvt_pk_bf16_f32 v89, v48, v49
	v_lshrrev_b32_e32 v48, 2, v0
	v_add_u32_e32 v48, 0x1a300, v48
	ds_read_b32 v48, v48 offset:4
	v_lshl_add_u64 v[46:47], v[46:47], 1, s[56:57]
	v_lshl_add_u64 v[46:47], v[158:159], 1, v[46:47]
	global_store_dwordx4 v[46:47], v[86:89], off sc1
	s_waitcnt lgkmcnt(0)
	v_mov_b32_e32 v0, v48
	v_pk_mul_f32 v[48:49], v[42:43], v[0:1] op_sel_hi:[1,0]
	v_pk_mul_f32 v[42:43], v[44:45], v[0:1] op_sel_hi:[1,0]
	v_pk_mul_f32 v[44:45], v[58:59], v[48:49]
	v_pk_mul_f32 v[48:49], v[38:39], v[0:1] op_sel_hi:[1,0]
	v_pk_mul_f32 v[38:39], v[40:41], v[0:1] op_sel_hi:[1,0]
	v_pk_mul_f32 v[42:43], v[60:61], v[42:43]
	v_pk_mul_f32 v[38:39], v[56:57], v[38:39]
	v_pk_mul_f32 v[40:41], v[54:55], v[48:49]
	s_and_b64 vcc, exec, s[6:7]
	s_cbranch_vccnz .LBB0_342
	ds_bpermute_b32 v48, v172, v44
	ds_bpermute_b32 v49, v172, v45
	ds_bpermute_b32 v50, v172, v40
	ds_bpermute_b32 v52, v172, v42
	ds_bpermute_b32 v53, v172, v43
	ds_bpermute_b32 v51, v172, v41
	ds_bpermute_b32 v86, v172, v38
	ds_bpermute_b32 v87, v172, v39
	s_waitcnt lgkmcnt(6)
	v_pk_mul_f32 v[48:49], v[82:83], v[48:49]
	s_waitcnt lgkmcnt(3)
	v_pk_mul_f32 v[52:53], v[84:85], v[52:53]
	s_waitcnt vmcnt(2)
	v_pk_fma_f32 v[44:45], v[74:75], v[44:45], v[48:49]
	s_waitcnt lgkmcnt(2)
	v_pk_mul_f32 v[48:49], v[80:81], v[50:51]
	s_waitcnt lgkmcnt(0)
	v_pk_mul_f32 v[50:51], v[78:79], v[86:87]
	v_pk_fma_f32 v[42:43], v[76:77], v[42:43], v[52:53]
	s_waitcnt vmcnt(1)
	v_pk_fma_f32 v[38:39], v[72:73], v[38:39], v[50:51]
	v_pk_fma_f32 v[40:41], v[70:71], v[40:41], v[48:49]
.LBB0_342:
	v_cvt_pk_bf16_f32 v48, v44, v45
	v_cvt_pk_bf16_f32 v49, v42, v43
	s_nop 0
	v_cvt_pk_bf16_f32 v50, v40, v41
	v_cvt_pk_bf16_f32 v51, v38, v39
	global_store_dwordx4 v[46:47], v[48:51], off offset:256 sc1
	s_waitcnt vmcnt(2)
	v_add_u32_e32 v72, 0xa0, v173
	v_add_u32_e32 v70, s77, v72
	s_and_b64 vcc, exec, s[6:7]
	v_ashrrev_i32_e32 v71, 31, v70
	s_cbranch_vccz .LBB0_344
	v_mov_b32_e32 v50, 0
	v_mov_b32_e32 v42, 1.0
	v_mov_b32_e32 v43, v42
	v_mov_b32_e32 v44, v42
	v_mov_b32_e32 v45, v42
	v_mov_b32_e32 v38, v42
	v_mov_b32_e32 v39, v42
	v_mov_b32_e32 v40, v42
	v_mov_b32_e32 v41, v42
	v_mov_b32_e32 v51, v50
	v_mov_b32_e32 v52, v50
	v_mov_b32_e32 v53, v50
	v_mov_b32_e32 v48, v50
	v_mov_b32_e32 v49, v50
	v_mov_b32_e32 v46, v50
	v_mov_b32_e32 v47, v50
	s_branch .LBB0_345

.LBB0_347:
	v_mad_u64_u32 v[30:31], s[8:9], v70, s20, 0
	v_mov_b32_e32 v70, v31
	v_mad_u64_u32 v[70:71], s[8:9], v71, s20, v[70:71]
	v_add_u32_e32 v0, s33, v0
	v_mov_b32_e32 v31, v70
	v_cvt_pk_bf16_f32 v70, v36, v37
	v_cvt_pk_bf16_f32 v71, v34, v35
	v_cvt_pk_bf16_f32 v72, v72, v73
	v_cvt_pk_bf16_f32 v73, v32, v33
	v_lshrrev_b32_e32 v32, 2, v0
	v_add_u32_e32 v32, 0x1a300, v32
	ds_read_b32 v32, v32 offset:4
	v_lshl_add_u64 v[30:31], v[30:31], 1, s[56:57]
	v_lshl_add_u64 v[30:31], v[158:159], 1, v[30:31]
	global_store_dwordx4 v[30:31], v[70:73], off sc1
	s_waitcnt lgkmcnt(0)
	v_mov_b32_e32 v0, v32
	v_pk_mul_f32 v[32:33], v[26:27], v[0:1] op_sel_hi:[1,0]
	v_pk_mul_f32 v[26:27], v[28:29], v[0:1] op_sel_hi:[1,0]
	v_pk_mul_f32 v[28:29], v[58:59], v[32:33]
	v_pk_mul_f32 v[32:33], v[22:23], v[0:1] op_sel_hi:[1,0]
	v_pk_mul_f32 v[22:23], v[24:25], v[0:1] op_sel_hi:[1,0]
	v_pk_mul_f32 v[26:27], v[60:61], v[26:27]
	v_pk_mul_f32 v[22:23], v[56:57], v[22:23]
	v_pk_mul_f32 v[24:25], v[54:55], v[32:33]
	s_and_b64 vcc, exec, s[6:7]
	s_cbranch_vccnz .LBB0_349
	ds_bpermute_b32 v32, v172, v28
	ds_bpermute_b32 v33, v172, v29
	ds_bpermute_b32 v34, v172, v24
	ds_bpermute_b32 v36, v172, v26
	ds_bpermute_b32 v37, v172, v27
	ds_bpermute_b32 v35, v172, v25
	ds_bpermute_b32 v70, v172, v22
	ds_bpermute_b32 v71, v172, v23
	s_waitcnt lgkmcnt(6)
	v_pk_mul_f32 v[32:33], v[50:51], v[32:33]
	s_waitcnt lgkmcnt(3)
	v_pk_mul_f32 v[36:37], v[52:53], v[36:37]
	s_waitcnt vmcnt(2)
	v_pk_fma_f32 v[28:29], v[42:43], v[28:29], v[32:33]
	s_waitcnt lgkmcnt(2)
	v_pk_mul_f32 v[32:33], v[48:49], v[34:35]
	s_waitcnt lgkmcnt(0)
	v_pk_mul_f32 v[34:35], v[46:47], v[70:71]
	v_pk_fma_f32 v[26:27], v[44:45], v[26:27], v[36:37]
	s_waitcnt vmcnt(1)
	v_pk_fma_f32 v[22:23], v[40:41], v[22:23], v[34:35]
	v_pk_fma_f32 v[24:25], v[38:39], v[24:25], v[32:33]
.LBB0_349:
	s_waitcnt vmcnt(1)
	v_add_u32_e32 v40, 0xb0, v173
	v_add_u32_e32 v38, s77, v40
	s_and_b64 vcc, exec, s[6:7]
	v_ashrrev_i32_e32 v39, 31, v38
	v_cvt_pk_bf16_f32 v32, v28, v29
	v_cvt_pk_bf16_f32 v33, v26, v27
	v_cvt_pk_bf16_f32 v34, v24, v25
	v_cvt_pk_bf16_f32 v35, v22, v23
	global_store_dwordx4 v[30:31], v[32:35], off offset:256 sc1
	s_cbranch_vccz .LBB0_351
	s_nop 0
	v_mov_b32_e32 v34, 0
	v_mov_b32_e32 v26, 1.0
	v_mov_b32_e32 v27, v26
	v_mov_b32_e32 v28, v26
	v_mov_b32_e32 v29, v26
	v_mov_b32_e32 v22, v26
	v_mov_b32_e32 v23, v26
	v_mov_b32_e32 v24, v26
	v_mov_b32_e32 v25, v26
	v_mov_b32_e32 v35, v34
	v_mov_b32_e32 v36, v34
	v_mov_b32_e32 v37, v34
	v_mov_b32_e32 v32, v34
	v_mov_b32_e32 v33, v34
	v_mov_b32_e32 v30, v34
	v_mov_b32_e32 v31, v34
	s_branch .LBB0_352

.LBB0_354:
	v_mad_u64_u32 v[10:11], s[4:5], v38, s20, 0
	v_mov_b32_e32 v38, v11
	v_mad_u64_u32 v[38:39], s[4:5], v39, s20, v[38:39]
	v_add_u32_e32 v0, s33, v0
	v_mov_b32_e32 v11, v38
	v_cvt_pk_bf16_f32 v38, v20, v21
	v_cvt_pk_bf16_f32 v39, v18, v19
	v_cvt_pk_bf16_f32 v40, v40, v41
	v_cvt_pk_bf16_f32 v41, v12, v13
	v_lshrrev_b32_e32 v18, 2, v0
	v_add_u32_e32 v18, 0x1a300, v18
	ds_read_b32 v18, v18 offset:4
	v_lshl_add_u64 v[10:11], v[10:11], 1, s[56:57]
	v_lshl_add_u64 v[10:11], v[158:159], 1, v[10:11]
	global_store_dwordx4 v[10:11], v[38:41], off sc1
	s_waitcnt lgkmcnt(0)
	v_mov_b32_e32 v0, v18
	v_pk_mul_f32 v[12:13], v[6:7], v[0:1] op_sel_hi:[1,0]
	v_pk_mul_f32 v[6:7], v[8:9], v[0:1] op_sel_hi:[1,0]
	v_pk_mul_f32 v[8:9], v[58:59], v[12:13]
	v_pk_mul_f32 v[12:13], v[2:3], v[0:1] op_sel_hi:[1,0]
	v_pk_mul_f32 v[2:3], v[4:5], v[0:1] op_sel_hi:[1,0]
	v_pk_mul_f32 v[6:7], v[60:61], v[6:7]
	v_pk_mul_f32 v[2:3], v[56:57], v[2:3]
	v_pk_mul_f32 v[4:5], v[54:55], v[12:13]
	s_and_b64 vcc, exec, s[6:7]
	s_cbranch_vccnz .LBB0_356
	ds_bpermute_b32 v12, v172, v8
	ds_bpermute_b32 v13, v172, v9
	ds_bpermute_b32 v18, v172, v4
	ds_bpermute_b32 v20, v172, v6
	ds_bpermute_b32 v21, v172, v7
	ds_bpermute_b32 v19, v172, v5
	ds_bpermute_b32 v38, v172, v2
	ds_bpermute_b32 v39, v172, v3
	s_waitcnt lgkmcnt(6)
	v_pk_mul_f32 v[12:13], v[34:35], v[12:13]
	s_waitcnt lgkmcnt(3)
	v_pk_mul_f32 v[20:21], v[36:37], v[20:21]
	s_waitcnt vmcnt(2)
	v_pk_fma_f32 v[8:9], v[26:27], v[8:9], v[12:13]
	s_waitcnt lgkmcnt(2)
	v_pk_mul_f32 v[12:13], v[32:33], v[18:19]
	s_waitcnt lgkmcnt(0)
	v_pk_mul_f32 v[18:19], v[30:31], v[38:39]
	v_pk_fma_f32 v[6:7], v[28:29], v[6:7], v[20:21]
	s_waitcnt vmcnt(1)
	v_pk_fma_f32 v[2:3], v[24:25], v[2:3], v[18:19]
	v_pk_fma_f32 v[4:5], v[22:23], v[4:5], v[12:13]
.LBB0_356:
	v_cvt_pk_bf16_f32 v18, v8, v9
	v_cvt_pk_bf16_f32 v19, v6, v7
	s_nop 0
	v_cvt_pk_bf16_f32 v20, v4, v5
	v_cvt_pk_bf16_f32 v21, v2, v3
	global_store_dwordx4 v[10:11], v[18:21], off offset:256 sc1
	s_andn2_b64 vcc, exec, s[80:81]
	s_mov_b64 s[4:5], -1
	s_cbranch_vccnz .LBB0_240

.LBB0_1235:
	s_waitcnt lgkmcnt(0)
	v_lshl_add_u64 v[10:11], s[46:47], 0, v[2:3]
	s_mov_b32 s1, 0x3c800000
	v_add_co_u32_e64 v26, s[4:5], s1, v10
	s_mov_b32 s2, 0x3e800000
	s_nop 0
	v_addc_co_u32_e64 v27, s[4:5], 0, v11, s[4:5]
	v_add_co_u32_e64 v28, s[4:5], s2, v10
	s_mov_b32 s3, 0x1e800000
	s_nop 0
	v_addc_co_u32_e64 v29, s[4:5], 0, v11, s[4:5]
	v_add_co_u32_e64 v30, s[4:5], 4.0, v10
	v_lshl_add_u64 v[12:13], s[46:47], 0, v[4:5]
	s_nop 0
	v_addc_co_u32_e64 v31, s[4:5], 0, v11, s[4:5]
	v_add_co_u32_e64 v10, s[4:5], s3, v10
	s_mov_b32 s6, 0x400000
	s_nop 0
	v_addc_co_u32_e64 v11, s[4:5], 0, v11, s[4:5]
	v_lshl_add_u64 v[8:9], s[46:47], 0, v[6:7]
	v_add_co_u32_e64 v32, s[4:5], s6, v12
	s_mov_b32 s7, 0x480000
	v_add_co_u32_e32 v22, vcc, 0x400000, v8
	v_addc_co_u32_e64 v33, s[4:5], 0, v13, s[4:5]
	v_add_co_u32_e64 v34, s[4:5], s7, v12
	v_addc_co_u32_e32 v23, vcc, 0, v9, vcc
	s_mov_b32 s9, 0x500000
	v_addc_co_u32_e64 v35, s[4:5], 0, v13, s[4:5]
	v_add_co_u32_e32 v24, vcc, 0x480000, v8
	v_add_co_u32_e64 v36, s[4:5], s9, v12
	s_nop 0
	v_addc_co_u32_e32 v25, vcc, 0, v9, vcc
	v_addc_co_u32_e64 v37, s[4:5], 0, v13, s[4:5]
	global_load_dwordx4 v[12:15], v[28:29], off
	global_load_dwordx4 v[18:21], v[30:31], off
	global_load_dword v0, v[22:23], off
	v_add_co_u32_e32 v8, vcc, 0x500000, v8
	s_add_i32 s0, s0, s8
	s_nop 0
	v_addc_co_u32_e32 v9, vcc, 0, v9, vcc
	global_load_dword v17, v[24:25], off
	global_load_dword v48, v[8:9], off
	s_nop 0
	global_load_dwordx4 v[22:25], v[26:27], off
	v_lshl_add_u64 v[2:3], v[2:3], 0, s[48:49]
	v_lshl_add_u64 v[4:5], v[4:5], 0, s[50:51]
	v_lshl_add_u64 v[6:7], v[6:7], 0, s[50:51]
	s_cmpk_lt_i32 s0, 0x4000
	s_waitcnt vmcnt(4)
	v_lshlrev_b32_e32 v42, 16, v20
	v_lshlrev_b32_e32 v8, 16, v12
	v_and_b32_e32 v9, 0xffff0000, v12
	v_lshlrev_b32_e32 v12, 16, v13
	v_and_b32_e32 v13, 0xffff0000, v13
	v_lshlrev_b32_e32 v38, 16, v14
	s_waitcnt vmcnt(1)
	v_max3_f32 v49, v0, v17, v48
	v_sub_f32_e32 v0, v0, v49
	v_sub_f32_e32 v17, v17, v49
	v_sub_f32_e32 v48, v48, v49
	v_mul_f32_e32 v49, 0x3fb8aa3b, v0
	v_mul_f32_e32 v50, 0x3fb8aa3b, v17
	v_mul_f32_e32 v51, 0x3fb8aa3b, v48
	v_fma_f32 v52, v0, s72, -v49
	v_rndne_f32_e32 v53, v49
	v_fma_f32 v54, v17, s72, -v50
	v_rndne_f32_e32 v55, v50
	v_fma_f32 v56, v48, s72, -v51
	v_rndne_f32_e32 v57, v51
	v_fmac_f32_e32 v52, 0x32a5705f, v0
	v_sub_f32_e32 v49, v49, v53
	v_fmac_f32_e32 v54, 0x32a5705f, v17
	v_sub_f32_e32 v50, v50, v55
	v_fmac_f32_e32 v56, 0x32a5705f, v48
	v_sub_f32_e32 v51, v51, v57
	v_add_f32_e32 v49, v49, v52
	v_add_f32_e32 v50, v50, v54
	v_cvt_i32_f32_e32 v53, v53
	v_cvt_i32_f32_e32 v55, v55
	v_add_f32_e32 v51, v51, v56
	v_exp_f32_e32 v49, v49
	v_exp_f32_e32 v50, v50
	v_cvt_i32_f32_e32 v57, v57
	v_exp_f32_e32 v51, v51
	v_ldexp_f32 v49, v49, v53
	v_ldexp_f32 v50, v50, v55
	v_cmp_ngt_f32_e32 vcc, s73, v17
	v_cmp_ngt_f32_e64 s[6:7], s73, v0
	v_ldexp_f32 v51, v51, v57
	v_cmp_ngt_f32_e64 s[4:5], s73, v48
	v_cndmask_b32_e64 v49, 0, v49, s[6:7]
	v_cndmask_b32_e32 v50, 0, v50, vcc
	v_cmp_nlt_f32_e32 vcc, s74, v17
	v_cmp_nlt_f32_e64 s[6:7], s74, v0
	v_cndmask_b32_e64 v17, 0, v51, s[4:5]
	v_cmp_nlt_f32_e64 s[4:5], s74, v48
	v_cndmask_b32_e64 v0, v237, v49, s[6:7]
	v_cndmask_b32_e32 v48, v237, v50, vcc
	v_and_b32_e32 v39, 0xffff0000, v14
	v_lshlrev_b32_e32 v14, 16, v15
	v_and_b32_e32 v15, 0xffff0000, v15
	v_cndmask_b32_e64 v50, v237, v17, s[4:5]
	v_add_f32_e32 v17, v0, v48
	s_waitcnt vmcnt(0)
	v_lshlrev_b32_e32 v44, 16, v22
	v_and_b32_e32 v45, 0xffff0000, v22
	v_lshlrev_b32_e32 v22, 16, v23
	v_and_b32_e32 v23, 0xffff0000, v23
	v_lshlrev_b32_e32 v46, 16, v24
	v_and_b32_e32 v47, 0xffff0000, v24
	v_lshlrev_b32_e32 v24, 16, v25
	v_and_b32_e32 v25, 0xffff0000, v25
	v_pk_mul_f32 v[8:9], v[48:49], v[8:9] op_sel_hi:[0,1]
	v_pk_mul_f32 v[12:13], v[48:49], v[12:13] op_sel_hi:[0,1]
	v_pk_mul_f32 v[38:39], v[48:49], v[38:39] op_sel_hi:[0,1]
	v_pk_mul_f32 v[14:15], v[48:49], v[14:15] op_sel_hi:[0,1]
	v_add_f32_e32 v17, v50, v17
	v_and_b32_e32 v43, 0xffff0000, v20
	v_lshlrev_b32_e32 v20, 16, v21
	v_and_b32_e32 v21, 0xffff0000, v21
	v_pk_fma_f32 v[12:13], v[0:1], v[22:23], v[12:13] op_sel_hi:[0,1,1]
	v_pk_fma_f32 v[8:9], v[0:1], v[44:45], v[8:9] op_sel_hi:[0,1,1]
	v_pk_fma_f32 v[14:15], v[0:1], v[24:25], v[14:15] op_sel_hi:[0,1,1]
	v_pk_fma_f32 v[22:23], v[0:1], v[46:47], v[38:39] op_sel_hi:[0,1,1]
	v_div_scale_f32 v0, s[2:3], v17, v17, 1.0
	v_pk_fma_f32 v[14:15], v[50:51], v[20:21], v[14:15] op_sel_hi:[0,1,1]
	v_rcp_f32_e32 v20, v0
	v_div_scale_f32 v24, vcc, 1.0, v17, 1.0
	v_lshlrev_b32_e32 v40, 16, v18
	v_fma_f32 v21, -v0, v20, 1.0
	v_fmac_f32_e32 v20, v21, v20
	v_and_b32_e32 v41, 0xffff0000, v18
	v_lshlrev_b32_e32 v18, 16, v19
	v_and_b32_e32 v19, 0xffff0000, v19
	v_mul_f32_e32 v21, v24, v20
	v_pk_fma_f32 v[12:13], v[50:51], v[18:19], v[12:13] op_sel_hi:[0,1,1]
	v_pk_fma_f32 v[18:19], v[50:51], v[42:43], v[22:23] op_sel_hi:[0,1,1]
	v_fma_f32 v22, -v0, v21, v24
	v_fmac_f32_e32 v21, v22, v20
	v_fma_f32 v0, -v0, v21, v24
	v_div_fmas_f32 v0, v0, v20, v21
	v_div_fixup_f32 v0, v0, v17, 1.0
	v_pk_fma_f32 v[8:9], v[50:51], v[40:41], v[8:9] op_sel_hi:[0,1,1]
	v_pk_mul_f32 v[20:21], v[0:1], v[12:13] op_sel_hi:[0,1]
	v_pk_mul_f32 v[22:23], v[0:1], v[14:15] op_sel_hi:[0,1]
	v_pk_mul_f32 v[14:15], v[0:1], v[18:19] op_sel_hi:[0,1]
	v_pk_mul_f32 v[8:9], v[0:1], v[8:9] op_sel_hi:[0,1]
	v_cvt_pk_bf16_f32 v12, v8, v9
	v_cvt_pk_bf16_f32 v13, v20, v21
	v_cvt_pk_bf16_f32 v14, v14, v15
	v_cvt_pk_bf16_f32 v15, v22, v23
	global_load_dwordx4 v[18:21], v[26:27], off offset:1024
	global_load_dwordx4 v[22:25], v[28:29], off offset:1024
	s_waitcnt vmcnt(1)
	v_lshlrev_b32_e32 v8, 16, v18
	global_store_dwordx4 v[10:11], v[12:15], off sc1
	global_load_dword v0, v[32:33], off
	global_load_dword v17, v[34:35], off
	s_nop 0
	global_load_dword v36, v[36:37], off
	s_nop 0
	global_load_dwordx4 v[12:15], v[30:31], off offset:1024
	s_waitcnt vmcnt(5)
	v_lshlrev_b32_e32 v28, 16, v22
	v_and_b32_e32 v29, 0xffff0000, v22
	v_lshlrev_b32_e32 v22, 16, v23
	v_and_b32_e32 v23, 0xffff0000, v23
	v_lshlrev_b32_e32 v30, 16, v24
	v_and_b32_e32 v31, 0xffff0000, v24
	v_lshlrev_b32_e32 v24, 16, v25
	v_and_b32_e32 v25, 0xffff0000, v25
	v_and_b32_e32 v9, 0xffff0000, v18
	v_lshlrev_b32_e32 v18, 16, v19
	v_and_b32_e32 v19, 0xffff0000, v19
	v_lshlrev_b32_e32 v26, 16, v20
	v_and_b32_e32 v27, 0xffff0000, v20
	v_lshlrev_b32_e32 v20, 16, v21
	v_and_b32_e32 v21, 0xffff0000, v21
	s_waitcnt vmcnt(1)
	v_max3_f32 v37, v0, v17, v36
	v_sub_f32_e32 v0, v0, v37
	v_sub_f32_e32 v17, v17, v37
	v_sub_f32_e32 v36, v36, v37
	v_mul_f32_e32 v37, 0x3fb8aa3b, v0
	v_mul_f32_e32 v38, 0x3fb8aa3b, v17
	v_mul_f32_e32 v39, 0x3fb8aa3b, v36
	v_fma_f32 v40, v0, s72, -v37
	v_rndne_f32_e32 v41, v37
	v_fma_f32 v42, v17, s72, -v38
	v_rndne_f32_e32 v43, v38
	v_fma_f32 v44, v36, s72, -v39
	v_rndne_f32_e32 v45, v39
	v_fmac_f32_e32 v40, 0x32a5705f, v0
	v_sub_f32_e32 v37, v37, v41
	v_fmac_f32_e32 v42, 0x32a5705f, v17
	v_sub_f32_e32 v38, v38, v43
	v_fmac_f32_e32 v44, 0x32a5705f, v36
	v_sub_f32_e32 v39, v39, v45
	v_add_f32_e32 v37, v37, v40
	v_add_f32_e32 v38, v38, v42
	v_cvt_i32_f32_e32 v41, v41
	v_cvt_i32_f32_e32 v43, v43
	v_add_f32_e32 v39, v39, v44
	v_exp_f32_e32 v37, v37
	v_exp_f32_e32 v38, v38
	v_cvt_i32_f32_e32 v45, v45
	v_exp_f32_e32 v39, v39
	v_ldexp_f32 v37, v37, v41
	v_ldexp_f32 v38, v38, v43
	v_cmp_ngt_f32_e32 vcc, s73, v17
	v_cmp_ngt_f32_e64 s[6:7], s73, v0
	v_ldexp_f32 v39, v39, v45
	v_cmp_ngt_f32_e64 s[4:5], s73, v36
	v_cndmask_b32_e64 v37, 0, v37, s[6:7]
	v_cndmask_b32_e32 v38, 0, v38, vcc
	v_cmp_nlt_f32_e32 vcc, s74, v17
	v_cmp_nlt_f32_e64 s[6:7], s74, v0
	v_cndmask_b32_e64 v17, 0, v39, s[4:5]
	v_cmp_nlt_f32_e64 s[4:5], s74, v36
	v_cndmask_b32_e64 v0, v237, v37, s[6:7]
	v_cndmask_b32_e32 v36, v237, v38, vcc
	v_cndmask_b32_e64 v38, v237, v17, s[4:5]
	v_add_f32_e32 v17, v0, v36
	v_pk_mul_f32 v[28:29], v[36:37], v[28:29] op_sel_hi:[0,1]
	v_pk_mul_f32 v[22:23], v[36:37], v[22:23] op_sel_hi:[0,1]
	v_pk_mul_f32 v[30:31], v[36:37], v[30:31] op_sel_hi:[0,1]
	v_pk_mul_f32 v[24:25], v[36:37], v[24:25] op_sel_hi:[0,1]
	v_add_f32_e32 v17, v38, v17
	s_waitcnt vmcnt(0)
	v_lshlrev_b32_e32 v34, 16, v14
	v_and_b32_e32 v35, 0xffff0000, v14
	v_lshlrev_b32_e32 v14, 16, v15
	v_and_b32_e32 v15, 0xffff0000, v15
	v_pk_fma_f32 v[18:19], v[0:1], v[18:19], v[22:23] op_sel_hi:[0,1,1]
	v_pk_fma_f32 v[8:9], v[0:1], v[8:9], v[28:29] op_sel_hi:[0,1,1]
	v_pk_fma_f32 v[20:21], v[0:1], v[20:21], v[24:25] op_sel_hi:[0,1,1]
	v_pk_fma_f32 v[22:23], v[0:1], v[26:27], v[30:31] op_sel_hi:[0,1,1]
	v_div_scale_f32 v0, s[2:3], v17, v17, 1.0
	v_pk_fma_f32 v[14:15], v[38:39], v[14:15], v[20:21] op_sel_hi:[0,1,1]
	v_rcp_f32_e32 v20, v0
	v_div_scale_f32 v24, vcc, 1.0, v17, 1.0
	v_lshlrev_b32_e32 v32, 16, v12
	v_fma_f32 v21, -v0, v20, 1.0
	v_fmac_f32_e32 v20, v21, v20
	v_and_b32_e32 v33, 0xffff0000, v12
	v_lshlrev_b32_e32 v12, 16, v13
	v_and_b32_e32 v13, 0xffff0000, v13
	v_mul_f32_e32 v21, v24, v20
	v_pk_fma_f32 v[12:13], v[38:39], v[12:13], v[18:19] op_sel_hi:[0,1,1]
	v_pk_fma_f32 v[18:19], v[38:39], v[34:35], v[22:23] op_sel_hi:[0,1,1]
	v_fma_f32 v22, -v0, v21, v24
	v_fmac_f32_e32 v21, v22, v20
	v_fma_f32 v0, -v0, v21, v24
	v_div_fmas_f32 v0, v0, v20, v21
	v_div_fixup_f32 v0, v0, v17, 1.0
	v_pk_fma_f32 v[8:9], v[38:39], v[32:33], v[8:9] op_sel_hi:[0,1,1]
	v_pk_mul_f32 v[22:23], v[0:1], v[14:15] op_sel_hi:[0,1]
	v_pk_mul_f32 v[14:15], v[0:1], v[18:19] op_sel_hi:[0,1]
	v_pk_mul_f32 v[20:21], v[0:1], v[12:13] op_sel_hi:[0,1]
	v_pk_mul_f32 v[8:9], v[0:1], v[8:9] op_sel_hi:[0,1]
	v_cvt_pk_bf16_f32 v12, v8, v9
	v_cvt_pk_bf16_f32 v13, v20, v21
	v_cvt_pk_bf16_f32 v14, v14, v15
	v_cvt_pk_bf16_f32 v15, v22, v23
	global_store_dwordx4 v[10:11], v[12:15], off offset:1024 sc1
	s_cbranch_scc1 .LBB0_1235
